# LRU loops no longer wait behind own stores/atomics, branch-free next-chunk prefetch, attention row-max via v_max3 tree (no canonicalising self-max)
# speedup vs baseline: 1.0087x; 1.0087x over previous
.Llru1_waited:
	v_lshlrev_b32_e32 v110, 16, v76
	v_and_b32_e32 v111, 0xffff0000, v76
	v_pk_fma_f32 v[110:111], v[68:69], v[110:111], v[72:73]
	v_lshlrev_b32_e32 v112, 16, v77
	v_and_b32_e32 v113, 0xffff0000, v77
	v_lshlrev_b32_e32 v118, 16, v24
	v_and_b32_e32 v119, 0xffff0000, v24
	v_pk_fma_f32 v[112:113], v[70:71], v[112:113], v[74:75]
	v_lshlrev_b32_e32 v114, 16, v78
	v_and_b32_e32 v115, 0xffff0000, v78
	v_pk_fma_f32 v[110:111], v[36:37], v[118:119], v[110:111]
	v_lshlrev_b32_e32 v118, 16, v25
	v_and_b32_e32 v119, 0xffff0000, v25
	v_pk_fma_f32 v[114:115], v[60:61], v[114:115], v[64:65]
	v_lshlrev_b32_e32 v116, 16, v79
	v_and_b32_e32 v117, 0xffff0000, v79
	v_pk_fma_f32 v[112:113], v[38:39], v[118:119], v[112:113]
	v_lshlrev_b32_e32 v118, 16, v26
	v_and_b32_e32 v119, 0xffff0000, v26
	v_pk_fma_f32 v[116:117], v[62:63], v[116:117], v[66:67]
	v_pk_fma_f32 v[114:115], v[44:45], v[118:119], v[114:115]
	v_lshlrev_b32_e32 v118, 16, v27
	v_and_b32_e32 v119, 0xffff0000, v27
	v_pk_fma_f32 v[116:117], v[46:47], v[118:119], v[116:117]
	v_lshlrev_b32_e32 v118, 16, v80
	v_and_b32_e32 v119, 0xffff0000, v80
	v_pk_fma_f32 v[110:111], v[40:41], v[118:119], v[110:111]
	v_lshlrev_b32_e32 v118, 16, v81
	v_and_b32_e32 v119, 0xffff0000, v81
	v_pk_fma_f32 v[112:113], v[42:43], v[118:119], v[112:113]
	v_lshlrev_b32_e32 v118, 16, v82
	v_and_b32_e32 v119, 0xffff0000, v82
	v_pk_fma_f32 v[114:115], v[48:49], v[118:119], v[114:115]
	v_lshlrev_b32_e32 v118, 16, v83
	v_and_b32_e32 v119, 0xffff0000, v83
	v_pk_fma_f32 v[116:117], v[50:51], v[118:119], v[116:117]
	v_lshlrev_b32_e32 v118, 16, v84
	v_and_b32_e32 v119, 0xffff0000, v84
	v_pk_fma_f32 v[110:111], v[52:53], v[118:119], v[110:111]
	v_lshlrev_b32_e32 v118, 16, v85
	v_and_b32_e32 v119, 0xffff0000, v85
	v_pk_fma_f32 v[112:113], v[54:55], v[118:119], v[112:113]
	v_lshlrev_b32_e32 v118, 16, v86
	v_and_b32_e32 v119, 0xffff0000, v86
	v_pk_fma_f32 v[114:115], v[56:57], v[118:119], v[114:115]
	v_lshlrev_b32_e32 v118, 16, v87
	v_and_b32_e32 v119, 0xffff0000, v87
	v_pk_fma_f32 v[116:117], v[58:59], v[118:119], v[116:117]
	v_add_u32_e32 v88, v134, v138
	ds_write_b128 v88, v[110:113] offset:17408
	ds_write_b128 v88, v[114:117] offset:17424
	v_cvt_pk_bf16_f32 v110, v110, v111
	v_cvt_pk_bf16_f32 v111, v112, v113
	v_cvt_pk_bf16_f32 v112, v114, v115
	v_cvt_pk_bf16_f32 v113, v116, v117
	ds_write_b128 v191, v[110:113]
	v_lshlrev_b32_e32 v110, 16, v92
	v_and_b32_e32 v111, 0xffff0000, v92
	v_pk_fma_f32 v[110:111], v[68:69], v[110:111], v[72:73]
	v_lshlrev_b32_e32 v112, 16, v93
	v_and_b32_e32 v113, 0xffff0000, v93
	v_lshlrev_b32_e32 v118, 16, v96
	v_and_b32_e32 v119, 0xffff0000, v96
	v_pk_fma_f32 v[112:113], v[70:71], v[112:113], v[74:75]
	v_lshlrev_b32_e32 v114, 16, v94
	v_and_b32_e32 v115, 0xffff0000, v94
	v_pk_fma_f32 v[110:111], v[36:37], v[118:119], v[110:111]
	v_lshlrev_b32_e32 v118, 16, v97
	v_and_b32_e32 v119, 0xffff0000, v97
	v_pk_fma_f32 v[114:115], v[60:61], v[114:115], v[64:65]
	v_lshlrev_b32_e32 v116, 16, v95
	v_and_b32_e32 v117, 0xffff0000, v95
	v_pk_fma_f32 v[112:113], v[38:39], v[118:119], v[112:113]
	v_lshlrev_b32_e32 v118, 16, v98
	v_and_b32_e32 v119, 0xffff0000, v98
	v_pk_fma_f32 v[116:117], v[62:63], v[116:117], v[66:67]
	v_pk_fma_f32 v[114:115], v[44:45], v[118:119], v[114:115]
	v_lshlrev_b32_e32 v118, 16, v99
	v_and_b32_e32 v119, 0xffff0000, v99
	v_pk_fma_f32 v[116:117], v[46:47], v[118:119], v[116:117]
	v_lshlrev_b32_e32 v118, 16, v100
	v_and_b32_e32 v119, 0xffff0000, v100
	v_pk_fma_f32 v[110:111], v[40:41], v[118:119], v[110:111]
	v_lshlrev_b32_e32 v118, 16, v101
	v_and_b32_e32 v119, 0xffff0000, v101
	v_pk_fma_f32 v[112:113], v[42:43], v[118:119], v[112:113]
	v_lshlrev_b32_e32 v118, 16, v102
	v_and_b32_e32 v119, 0xffff0000, v102
	v_pk_fma_f32 v[114:115], v[48:49], v[118:119], v[114:115]
	v_lshlrev_b32_e32 v118, 16, v103
	v_and_b32_e32 v119, 0xffff0000, v103
	v_pk_fma_f32 v[116:117], v[50:51], v[118:119], v[116:117]
	v_lshlrev_b32_e32 v118, 16, v104
	v_and_b32_e32 v119, 0xffff0000, v104
	v_pk_fma_f32 v[110:111], v[52:53], v[118:119], v[110:111]
	v_lshlrev_b32_e32 v118, 16, v105
	v_and_b32_e32 v119, 0xffff0000, v105
	v_pk_fma_f32 v[112:113], v[54:55], v[118:119], v[112:113]
	v_lshlrev_b32_e32 v118, 16, v106
	v_and_b32_e32 v119, 0xffff0000, v106
	v_pk_fma_f32 v[114:115], v[56:57], v[118:119], v[114:115]
	v_lshlrev_b32_e32 v118, 16, v107
	v_and_b32_e32 v119, 0xffff0000, v107
	v_pk_fma_f32 v[116:117], v[58:59], v[118:119], v[116:117]
	ds_write_b128 v192, v[110:113] offset:17408
	ds_write_b128 v192, v[114:117] offset:17424
	v_cvt_pk_bf16_f32 v110, v110, v111
	v_cvt_pk_bf16_f32 v111, v112, v113
	v_cvt_pk_bf16_f32 v112, v114, v115
	v_cvt_pk_bf16_f32 v113, v116, v117
	s_cmpk_eq_i32 s2, 0xe0
	ds_write_b128 v191, v[110:113] offset:8704
	s_cbranch_scc1 .LBB0_301
	s_add_i32 s0, s2, 32
	s_and_b32 s0, s0, 0x60
	s_add_i32 s0, s0, s87
	s_lshl_b32 s8, s0, 6
	s_and_b32 s5, s3, 0x6000
	s_cmp_eq_u32 s8, 0
	s_cbranch_scc1 .Llru1_pf_slow
	s_add_i32 s0, s8, s5
	v_add_u32_e32 v88, s0, v133
	v_lshlrev_b64 v[84:85], 11, v[88:89]
	s_mov_b64 s[0:1], 0x1000
	v_lshl_add_u64 v[84:85], v[126:127], 0, v[84:85]
	s_mov_b64 s[6:7], 0x10000
	v_lshl_add_u64 v[84:85], v[84:85], 0, s[0:1]
	v_lshl_add_u64 v[104:105], v[84:85], 0, s[6:7]
	global_load_dwordx4 v[76:79], v[84:85], off offset:-4096 nt
	global_load_dwordx4 v[24:27], v[84:85], off offset:-2048 nt
	global_load_dwordx4 v[80:83], v[84:85], off nt
	global_load_dwordx4 v[84:87], v[84:85], off offset:2048 nt
	global_load_dwordx4 v[92:95], v[104:105], off offset:-4096 nt
	global_load_dwordx4 v[96:99], v[104:105], off offset:-2048 nt
	global_load_dwordx4 v[100:103], v[104:105], off nt
	global_load_dwordx4 v[104:107], v[104:105], off offset:2048 nt
	s_branch .LBB0_301
.Llru1_pf_slow:
	v_mov_b32_e32 v26, v108
	v_mov_b32_e32 v27, v108
	v_add_u32_e32 v104, s8, v133
	v_mov_b32_e32 v24, v108
	v_mov_b32_e32 v25, v108
	v_mov_b64_e32 v[78:79], v[26:27]
	s_and_b32 s5, s3, 0x6000
	v_cmp_lt_i32_e64 s[0:1], -1, v104
	v_mov_b64_e32 v[76:77], v[24:25]
	s_and_saveexec_b64 s[6:7], s[0:1]
	s_cbranch_execz .LBB0_286
	v_add_u32_e32 v88, s5, v104
	v_lshlrev_b64 v[76:77], 11, v[88:89]
	v_lshl_add_u64 v[76:77], v[126:127], 0, v[76:77]
	global_load_dwordx4 v[76:79], v[76:77], off nt

.LBB0_301:
	s_waitcnt lgkmcnt(0)
	s_barrier
	ds_read_b128 v[110:113], v135
	ds_read_b128 v[114:117], v135 offset:4352
	ds_read_b128 v[122:125], v135 offset:8704
	ds_read_b128 v[194:197], v135 offset:13056
	s_waitcnt lgkmcnt(3)
	v_mfma_f32_16x16x32_bf16 v[118:121], v[110:113], v[0:3], 0
	v_mfma_f32_16x16x32_bf16 v[110:113], v[110:113], v[8:11], 0
	ds_read_b128 v[206:209], v135 offset:64
	s_waitcnt lgkmcnt(3)
	v_mfma_f32_16x16x32_bf16 v[198:201], v[114:117], v[0:3], 0
	v_mfma_f32_16x16x32_bf16 v[114:117], v[114:117], v[8:11], 0
	ds_read_b128 v[214:217], v135 offset:4416
	s_waitcnt lgkmcnt(3)
	v_mfma_f32_16x16x32_bf16 v[210:213], v[122:125], v[0:3], 0
	v_mfma_f32_16x16x32_bf16 v[122:125], v[122:125], v[8:11], 0
	ds_read_b128 v[222:225], v135 offset:8768
	s_waitcnt lgkmcnt(3)
	v_mfma_f32_16x16x32_bf16 v[218:221], v[194:197], v[0:3], 0
	v_mfma_f32_16x16x32_bf16 v[194:197], v[194:197], v[8:11], 0
	ds_read_b128 v[226:229], v135 offset:13120
	s_waitcnt lgkmcnt(3)
	v_mfma_f32_16x16x32_bf16 v[118:121], v[206:209], v[4:7], v[118:121]
	v_mfma_f32_16x16x32_bf16 v[110:113], v[206:209], v[12:15], v[110:113]
	ds_read_b128 v[206:209], v135 offset:128
	s_waitcnt lgkmcnt(3)
	v_mfma_f32_16x16x32_bf16 v[198:201], v[214:217], v[4:7], v[198:201]
	v_mfma_f32_16x16x32_bf16 v[114:117], v[214:217], v[12:15], v[114:117]
	ds_read_b128 v[214:217], v135 offset:4480
	s_waitcnt lgkmcnt(3)
	v_mfma_f32_16x16x32_bf16 v[210:213], v[222:225], v[4:7], v[210:213]
	v_mfma_f32_16x16x32_bf16 v[122:125], v[222:225], v[12:15], v[122:125]
	ds_read_b128 v[222:225], v135 offset:8832
	s_waitcnt lgkmcnt(3)
	v_mfma_f32_16x16x32_bf16 v[218:221], v[226:229], v[4:7], v[218:221]
	v_mfma_f32_16x16x32_bf16 v[194:197], v[226:229], v[12:15], v[194:197]
	ds_read_b128 v[226:229], v135 offset:13184
	s_waitcnt lgkmcnt(3)
	v_mfma_f32_16x16x32_bf16 v[118:121], v[206:209], v[16:19], v[118:121]
	v_mfma_f32_16x16x32_bf16 v[110:113], v[206:209], v[28:31], v[110:113]
	ds_read_b128 v[206:209], v135 offset:192
	s_waitcnt lgkmcnt(3)
	v_mfma_f32_16x16x32_bf16 v[198:201], v[214:217], v[16:19], v[198:201]
	v_mfma_f32_16x16x32_bf16 v[114:117], v[214:217], v[28:31], v[114:117]
	ds_read_b128 v[214:217], v135 offset:4544
	s_waitcnt lgkmcnt(3)
	v_mfma_f32_16x16x32_bf16 v[210:213], v[222:225], v[16:19], v[210:213]
	v_mfma_f32_16x16x32_bf16 v[222:225], v[222:225], v[28:31], v[122:125]
	ds_read_b128 v[230:233], v135 offset:8896
	s_waitcnt lgkmcnt(3)
	v_mfma_f32_16x16x32_bf16 v[218:221], v[226:229], v[16:19], v[218:221]
	v_mfma_f32_16x16x32_bf16 v[194:197], v[226:229], v[28:31], v[194:197]
	ds_read_b128 v[234:237], v135 offset:13248
	s_waitcnt lgkmcnt(3)
	v_mfma_f32_16x16x32_bf16 v[226:229], v[206:209], v[20:23], v[118:121]
	v_mfma_f32_16x16x32_bf16 v[206:209], v[206:209], v[32:35], v[110:113]
	s_waitcnt lgkmcnt(2)
	v_mfma_f32_16x16x32_bf16 v[198:201], v[214:217], v[20:23], v[198:201]
	v_mfma_f32_16x16x32_bf16 v[214:217], v[214:217], v[32:35], v[114:117]
	s_waitcnt lgkmcnt(1)
	v_mfma_f32_16x16x32_bf16 v[122:125], v[230:233], v[20:23], v[210:213]
	v_mfma_f32_16x16x32_bf16 v[118:121], v[230:233], v[32:35], v[222:225]
	s_waitcnt lgkmcnt(0)
	v_mfma_f32_16x16x32_bf16 v[114:117], v[234:237], v[20:23], v[218:221]
	v_mfma_f32_16x16x32_bf16 v[110:113], v[234:237], v[32:35], v[194:197]
	s_nop 2
	v_fma_f32 v194, -v226, s4, v90
	v_fma_f32 v195, -v227, s4, v91
	v_pk_fma_f32 v[196:197], v[206:207], s[4:5], v[128:129] op_sel_hi:[1,0,1] neg_lo:[1,0,0] neg_hi:[1,0,0]
	v_exp_f32_e32 v194, v194
	v_exp_f32_e32 v195, v195
	v_exp_f32_e32 v196, v196
	v_exp_f32_e32 v197, v197
	ds_read2st64_b32 v[206:207], v139 offset0:68 offset1:70
	v_pk_add_f32 v[194:195], v[194:195], 1.0 op_sel_hi:[1,0]
	v_pk_fma_f32 v[210:211], v[228:229], s[4:5], v[90:91] op_sel_hi:[1,0,1] neg_lo:[1,0,0] neg_hi:[1,0,0]
	v_rcp_f32_e32 v194, v194
	v_rcp_f32_e32 v195, v195
	v_pk_add_f32 v[196:197], v[196:197], 1.0 op_sel_hi:[1,0]
	v_pk_fma_f32 v[198:199], v[198:199], s[4:5], v[90:91] op_sel_hi:[1,0,1] neg_lo:[1,0,0] neg_hi:[1,0,0]
	v_rcp_f32_e32 v196, v196
	v_pk_mul_f32 v[194:195], v[130:131], v[194:195]
	v_rcp_f32_e32 v197, v197
	v_exp_f32_e32 v194, v194
	v_exp_f32_e32 v195, v195
	v_exp_f32_e32 v198, v198
	v_exp_f32_e32 v199, v199
	v_pk_fma_f32 v[200:201], v[200:201], s[4:5], v[90:91] op_sel_hi:[1,0,1] neg_lo:[1,0,0] neg_hi:[1,0,0]
	v_pk_fma_f32 v[202:203], v[194:195], v[194:195], 1.0 op_sel_hi:[1,1,0] neg_lo:[1,0,0] neg_hi:[1,0,0]
	v_exp_f32_e32 v200, v200
	v_sqrt_f32_e32 v202, v202
	v_sqrt_f32_e32 v203, v203
	v_exp_f32_e32 v201, v201
	v_pk_fma_f32 v[122:123], v[122:123], s[4:5], v[90:91] op_sel_hi:[1,0,1] neg_lo:[1,0,0] neg_hi:[1,0,0]
	v_pk_fma_f32 v[118:119], v[118:119], s[4:5], v[128:129] op_sel_hi:[1,0,1] neg_lo:[1,0,0] neg_hi:[1,0,0]
	v_pk_mul_f32 v[196:197], v[196:197], v[202:203]
	v_exp_f32_e32 v202, v210
	v_exp_f32_e32 v203, v211
	s_waitcnt lgkmcnt(0)
	v_pk_mul_f32 v[196:197], v[206:207], v[196:197]
	ds_write2st64_b32 v139, v194, v195 offset0:196 offset1:198
	ds_write_b32 v141, v197
	v_exp_f32_e32 v122, v122
	v_pk_add_f32 v[194:195], v[202:203], 1.0 op_sel_hi:[1,0]
	v_pk_fma_f32 v[202:203], v[208:209], s[4:5], v[128:129] op_sel_hi:[1,0,1] neg_lo:[1,0,0] neg_hi:[1,0,0]
	v_rcp_f32_e32 v194, v194
	v_rcp_f32_e32 v195, v195
	v_exp_f32_e32 v202, v202
	v_exp_f32_e32 v203, v203
	ds_read2st64_b32 v[208:209], v139 offset0:72 offset1:74
	v_pk_mul_f32 v[194:195], v[130:131], v[194:195]
	v_exp_f32_e32 v123, v123
	v_exp_f32_e32 v194, v194
	v_exp_f32_e32 v195, v195
	v_pk_add_f32 v[202:203], v[202:203], 1.0 op_sel_hi:[1,0]
	v_pk_add_f32 v[122:123], v[122:123], 1.0 op_sel_hi:[1,0]
	v_rcp_f32_e32 v202, v202
	v_pk_fma_f32 v[206:207], v[194:195], v[194:195], 1.0 op_sel_hi:[1,1,0] neg_lo:[1,0,0] neg_hi:[1,0,0]
	v_rcp_f32_e32 v203, v203
	v_sqrt_f32_e32 v206, v206
	v_sqrt_f32_e32 v207, v207
	v_rcp_f32_e32 v122, v122
	v_rcp_f32_e32 v123, v123
	v_exp_f32_e32 v118, v118
	v_pk_mul_f32 v[202:203], v[202:203], v[206:207]
	v_exp_f32_e32 v119, v119
	s_waitcnt lgkmcnt(0)
	v_pk_mul_f32 v[202:203], v[208:209], v[202:203]
	ds_write2st64_b32 v139, v194, v195 offset0:200 offset1:202
	ds_write_b32 v142, v202
	ds_write_b32 v143, v203
	v_pk_add_f32 v[194:195], v[198:199], 1.0 op_sel_hi:[1,0]
	v_pk_fma_f32 v[198:199], v[214:215], s[4:5], v[128:129] op_sel_hi:[1,0,1] neg_lo:[1,0,0] neg_hi:[1,0,0]
	v_rcp_f32_e32 v194, v194
	v_rcp_f32_e32 v195, v195
	v_exp_f32_e32 v198, v198
	v_exp_f32_e32 v199, v199
	ds_read2st64_b32 v[206:207], v139 offset0:100 offset1:102
	v_pk_mul_f32 v[194:195], v[130:131], v[194:195]
	v_pk_mul_f32 v[122:123], v[130:131], v[122:123]
	v_exp_f32_e32 v194, v194
	v_exp_f32_e32 v195, v195
	v_pk_add_f32 v[198:199], v[198:199], 1.0 op_sel_hi:[1,0]
	v_exp_f32_e32 v122, v122
	v_rcp_f32_e32 v198, v198
	v_pk_fma_f32 v[202:203], v[194:195], v[194:195], 1.0 op_sel_hi:[1,1,0] neg_lo:[1,0,0] neg_hi:[1,0,0]
	v_rcp_f32_e32 v199, v199
	v_sqrt_f32_e32 v202, v202
	v_sqrt_f32_e32 v203, v203
	v_exp_f32_e32 v123, v123
	v_pk_add_f32 v[118:119], v[118:119], 1.0 op_sel_hi:[1,0]
	v_pk_fma_f32 v[124:125], v[124:125], s[4:5], v[90:91] op_sel_hi:[1,0,1] neg_lo:[1,0,0] neg_hi:[1,0,0]
	v_pk_mul_f32 v[198:199], v[198:199], v[202:203]
	v_rcp_f32_e32 v118, v118
	s_waitcnt lgkmcnt(0)
	v_pk_mul_f32 v[198:199], v[206:207], v[198:199]
	ds_write2st64_b32 v139, v194, v195 offset0:228 offset1:230
	ds_write_b32 v144, v198
	ds_write_b32 v145, v199
	v_pk_add_f32 v[194:195], v[200:201], 1.0 op_sel_hi:[1,0]
	v_pk_fma_f32 v[198:199], v[216:217], s[4:5], v[128:129] op_sel_hi:[1,0,1] neg_lo:[1,0,0] neg_hi:[1,0,0]
	v_rcp_f32_e32 v194, v194
	v_rcp_f32_e32 v195, v195
	v_exp_f32_e32 v198, v198
	v_exp_f32_e32 v199, v199
	ds_read2st64_b32 v[202:203], v139 offset0:104 offset1:106
	v_pk_mul_f32 v[194:195], v[130:131], v[194:195]
	v_rcp_f32_e32 v119, v119
	v_exp_f32_e32 v194, v194
	v_exp_f32_e32 v195, v195
	v_pk_add_f32 v[198:199], v[198:199], 1.0 op_sel_hi:[1,0]
	v_exp_f32_e32 v124, v124
	v_rcp_f32_e32 v198, v198
	v_pk_fma_f32 v[200:201], v[194:195], v[194:195], 1.0 op_sel_hi:[1,1,0] neg_lo:[1,0,0] neg_hi:[1,0,0]
	v_rcp_f32_e32 v199, v199
	v_sqrt_f32_e32 v200, v200
	v_sqrt_f32_e32 v201, v201
	v_exp_f32_e32 v125, v125
	v_pk_fma_f32 v[114:115], v[114:115], s[4:5], v[90:91] op_sel_hi:[1,0,1] neg_lo:[1,0,0] neg_hi:[1,0,0]
	v_pk_fma_f32 v[120:121], v[120:121], s[4:5], v[128:129] op_sel_hi:[1,0,1] neg_lo:[1,0,0] neg_hi:[1,0,0]
	v_pk_mul_f32 v[198:199], v[198:199], v[200:201]
	v_exp_f32_e32 v114, v114
	s_waitcnt lgkmcnt(0)
	v_pk_mul_f32 v[198:199], v[198:199], v[202:203]
	ds_write2st64_b32 v139, v194, v195 offset0:232 offset1:234
	ds_write_b32 v146, v198
	ds_write_b32 v147, v199
	v_pk_fma_f32 v[194:195], v[122:123], v[122:123], 1.0 op_sel_hi:[1,1,0] neg_lo:[1,0,0] neg_hi:[1,0,0]
	ds_read2st64_b32 v[198:199], v139 offset0:132 offset1:134
	v_sqrt_f32_e32 v194, v194
	v_sqrt_f32_e32 v195, v195
	ds_write_b32 v140, v196
	ds_write_b32 v148, v122
	v_exp_f32_e32 v115, v115
	v_pk_mul_f32 v[118:119], v[118:119], v[194:195]
	v_exp_f32_e32 v120, v120
	s_waitcnt lgkmcnt(2)
	v_pk_mul_f32 v[118:119], v[118:119], v[198:199]
	ds_write_b32 v149, v123
	ds_write_b32 v150, v118
	ds_write_b32 v151, v119
	v_pk_add_f32 v[118:119], v[124:125], 1.0 op_sel_hi:[1,0]
	v_exp_f32_e32 v121, v121
	v_rcp_f32_e32 v118, v118
	v_rcp_f32_e32 v119, v119
	v_pk_add_f32 v[114:115], v[114:115], 1.0 op_sel_hi:[1,0]
	v_pk_add_f32 v[120:121], v[120:121], 1.0 op_sel_hi:[1,0]
	v_rcp_f32_e32 v114, v114
	v_pk_mul_f32 v[118:119], v[130:131], v[118:119]
	v_rcp_f32_e32 v115, v115
	v_exp_f32_e32 v118, v118
	v_exp_f32_e32 v119, v119
	v_rcp_f32_e32 v120, v120
	v_rcp_f32_e32 v121, v121
	ds_read2st64_b32 v[124:125], v139 offset0:136 offset1:138
	v_pk_fma_f32 v[122:123], v[118:119], v[118:119], 1.0 op_sel_hi:[1,1,0] neg_lo:[1,0,0] neg_hi:[1,0,0]
	v_pk_fma_f32 v[110:111], v[110:111], s[4:5], v[128:129] op_sel_hi:[1,0,1] neg_lo:[1,0,0] neg_hi:[1,0,0]
	v_sqrt_f32_e32 v122, v122
	v_sqrt_f32_e32 v123, v123
	v_pk_mul_f32 v[114:115], v[130:131], v[114:115]
	v_exp_f32_e32 v110, v110
	v_exp_f32_e32 v111, v111
	v_exp_f32_e32 v114, v114
	v_exp_f32_e32 v115, v115
	v_pk_mul_f32 v[120:121], v[120:121], v[122:123]
	ds_write_b32 v152, v118
	s_waitcnt lgkmcnt(1)
	v_pk_mul_f32 v[120:121], v[120:121], v[124:125]
	ds_write_b32 v153, v119
	ds_write_b32 v154, v120
	ds_write_b32 v155, v121
	v_pk_add_f32 v[110:111], v[110:111], 1.0 op_sel_hi:[1,0]
	v_pk_fma_f32 v[118:119], v[114:115], v[114:115], 1.0 op_sel_hi:[1,1,0] neg_lo:[1,0,0] neg_hi:[1,0,0]
	v_rcp_f32_e32 v110, v110
	v_rcp_f32_e32 v111, v111
	v_sqrt_f32_e32 v118, v118
	v_sqrt_f32_e32 v119, v119
	ds_read2st64_b32 v[120:121], v139 offset0:164 offset1:166
	v_pk_fma_f32 v[116:117], v[116:117], s[4:5], v[90:91] op_sel_hi:[1,0,1] neg_lo:[1,0,0] neg_hi:[1,0,0]
	ds_write_b32 v156, v114
	v_exp_f32_e32 v116, v116
	v_exp_f32_e32 v117, v117
	v_pk_mul_f32 v[110:111], v[110:111], v[118:119]
	v_pk_fma_f32 v[112:113], v[112:113], s[4:5], v[128:129] op_sel_hi:[1,0,1] neg_lo:[1,0,0] neg_hi:[1,0,0]
	s_waitcnt lgkmcnt(1)
	v_pk_mul_f32 v[110:111], v[110:111], v[120:121]
	ds_write_b32 v157, v115
	ds_write_b32 v158, v110
	ds_write_b32 v159, v111
	v_pk_add_f32 v[110:111], v[116:117], 1.0 op_sel_hi:[1,0]
	v_exp_f32_e32 v112, v112
	v_rcp_f32_e32 v110, v110
	v_rcp_f32_e32 v111, v111
	v_exp_f32_e32 v113, v113
	ds_read2st64_b32 v[116:117], v139 offset0:168 offset1:170
	v_pk_mul_f32 v[110:111], v[130:131], v[110:111]
	s_nop 0
	v_exp_f32_e32 v110, v110
	v_exp_f32_e32 v111, v111
	v_pk_add_f32 v[112:113], v[112:113], 1.0 op_sel_hi:[1,0]
	v_pk_fma_f32 v[114:115], v[110:111], v[110:111], 1.0 op_sel_hi:[1,1,0] neg_lo:[1,0,0] neg_hi:[1,0,0]
	v_rcp_f32_e32 v112, v112
	v_rcp_f32_e32 v113, v113
	v_sqrt_f32_e32 v114, v114
	v_sqrt_f32_e32 v115, v115
	s_nop 0
	v_pk_mul_f32 v[112:113], v[112:113], v[114:115]
	s_waitcnt lgkmcnt(0)
	v_pk_mul_f32 v[112:113], v[112:113], v[116:117]
	ds_write_b32 v160, v110
	ds_write_b32 v161, v111
	ds_write_b32 v162, v112
	ds_write_b32 v163, v113
	s_waitcnt lgkmcnt(0)
	s_barrier
	ds_read2st64_b32 v[110:111], v164 offset0:196 offset1:198
	ds_read2st64_b32 v[112:113], v164 offset0:200 offset1:202
	ds_read_b32 v88, v165
	ds_read_b32 v109, v166
	ds_read_b32 v114, v167
	ds_read_b32 v115, v168
	ds_read_b32 v116, v169
	ds_read_b32 v117, v170
	ds_read_b32 v118, v171
	ds_read_b32 v119, v172
	s_waitcnt lgkmcnt(7)
	v_fmac_f32_e32 v88, 0, v110
	s_waitcnt lgkmcnt(6)
	v_fmac_f32_e32 v109, v88, v111
	v_mul_f32_e32 v88, v110, v111
	ds_read2st64_b32 v[110:111], v164 offset0:204 offset1:206
	s_waitcnt lgkmcnt(6)
	v_fmac_f32_e32 v114, v109, v112
	v_mul_f32_e32 v88, v88, v112
	s_waitcnt lgkmcnt(5)
	v_fmac_f32_e32 v115, v114, v113
	v_mul_f32_e32 v88, v88, v113
	ds_read2st64_b32 v[112:113], v164 offset0:208 offset1:210
	s_waitcnt lgkmcnt(1)
	v_fmac_f32_e32 v116, v115, v110
	v_mul_f32_e32 v88, v88, v110
	v_fmac_f32_e32 v117, v116, v111
	v_mul_f32_e32 v88, v88, v111
	s_waitcnt lgkmcnt(0)
	v_fmac_f32_e32 v118, v117, v112
	v_mul_f32_e32 v88, v88, v112
	v_fmac_f32_e32 v119, v118, v113
	v_mul_f32_e32 v88, v88, v113
	ds_read2st64_b32 v[110:111], v164 offset0:212 offset1:214
	ds_read2st64_b32 v[112:113], v164 offset0:216 offset1:218
	ds_read_b32 v109, v173
	ds_read_b32 v114, v174
	ds_read_b32 v115, v175
	ds_read_b32 v116, v176
	ds_read_b32 v117, v177
	ds_read_b32 v118, v178
	ds_read_b32 v120, v179
	ds_read_b32 v121, v180
	s_waitcnt lgkmcnt(7)
	v_fmac_f32_e32 v109, v119, v110
	v_mul_f32_e32 v88, v88, v110
	s_waitcnt lgkmcnt(6)
	v_fmac_f32_e32 v114, v109, v111
	v_mul_f32_e32 v88, v88, v111
	ds_read2st64_b32 v[110:111], v164 offset0:220 offset1:222
	s_waitcnt lgkmcnt(6)
	v_fmac_f32_e32 v115, v114, v112
	v_mul_f32_e32 v88, v88, v112
	s_waitcnt lgkmcnt(5)
	v_fmac_f32_e32 v116, v115, v113
	v_mul_f32_e32 v88, v88, v113
	ds_read2st64_b32 v[112:113], v164 offset0:224 offset1:226
	s_waitcnt lgkmcnt(1)
	v_mul_f32_e32 v88, v88, v110
	v_fmac_f32_e32 v117, v116, v110
	v_mul_f32_e32 v88, v88, v111
	v_fmac_f32_e32 v118, v117, v111
	s_waitcnt lgkmcnt(0)
	v_mul_f32_e32 v88, v88, v112
	v_fmac_f32_e32 v120, v118, v112
	v_mul_f32_e32 v88, v88, v113
	v_fmac_f32_e32 v121, v120, v113
	ds_write_b32 v136, v88
	ds_write_b32 v137, v121
	s_waitcnt lgkmcnt(0)
	s_barrier
	s_and_saveexec_b64 s[0:1], vcc
	s_cbranch_execz .LBB0_282
	ds_read_b32 v88, v181
	ds_read_b32 v109, v182
	ds_read_b32 v110, v183
	ds_read_b32 v111, v184
	ds_read_b32 v112, v185
	ds_read_b32 v113, v186
	ds_read_b32 v114, v187
	ds_read_b32 v115, v189
	s_and_b32 s5, s2, 0x60
	s_add_i32 s5, s5, s87
	s_waitcnt lgkmcnt(6)
	v_fmac_f32_e32 v109, 0, v88
	s_waitcnt lgkmcnt(5)
	v_mul_f32_e32 v88, v88, v110
	s_and_b32 s6, s2, 0x80
	s_waitcnt lgkmcnt(3)
	v_mul_f32_e32 v88, v88, v112
	s_add_i32 s5, s5, s6
	v_fmac_f32_e32 v111, v109, v110
	s_waitcnt lgkmcnt(1)
	v_mul_f32_e32 v109, v88, v114
	v_lshl_or_b32 v88, s5, 10, v190
	v_fmac_f32_e32 v113, v111, v112
	v_lshlrev_b64 v[110:111], 2, v[88:89]
	s_waitcnt lgkmcnt(0)
	v_fmac_f32_e32 v115, v113, v114
	v_lshl_add_u64 v[112:113], s[80:81], 0, v[110:111]
	v_lshl_add_u64 v[110:111], s[82:83], 0, v[110:111]
	s_waitcnt vmcnt(0)
	global_store_dword v[112:113], v109, off
	global_store_dword v[110:111], v115, off
	s_or_b64 exec, exec, s[0:1]
	s_add_i32 s2, s2, 32
	s_addk_i32 s3, 0x800
	s_cmpk_lg_i32 s2, 0x100
	s_cbranch_scc0 .LBB0_303
	s_branch .Llru1_waited

.LBB0_383:
	s_or_b64 exec, exec, s[28:29]
	s_nop 6
	v_max3_f32 v0, v80, v81, v82
	v_max3_f32 v2, v83, v84, v85
	v_max3_f32 v3, v86, v87, v88
	v_max3_f32 v4, v89, v90, v91
	v_max3_f32 v5, v92, v93, v94
	v_max3_f32 v6, v95, v96, v97
	v_max3_f32 v7, v98, v99, v100
	v_max3_f32 v8, v101, v102, v103
	v_max3_f32 v9, v104, v105, v106
	v_max3_f32 v10, v107, v108, v109
	v_max3_f32 v11, v110, v111, v0
	v_max3_f32 v2, v2, v3, v4
	v_max3_f32 v5, v5, v6, v7
	v_max3_f32 v8, v8, v9, v10
	v_max3_f32 v2, v2, v5, v8
	v_max_f32_e32 v0, v2, v11
	v_mov_b32_e32 v2, v0
	s_nop 1
	v_permlane32_swap_b32_e32 v0, v2
	v_max3_f32 v222, v221, v0, v2
	v_sub_f32_e32 v0, v221, v222
	v_exp_f32_e32 v0, v0
	s_nop 0
	v_cmp_eq_f32_e32 vcc, 1.0, v0
	s_cmp_lg_u64 vcc, exec
	s_cselect_b64 s[28:29], -1, 0
	s_cmp_eq_u64 vcc, exec
	s_cbranch_scc1 .LBB0_385
	v_and_b32_e32 v4, 64, v188
	v_xor_b32_e32 v3, 16, v188
	v_add_u32_e32 v4, 64, v4
	v_cmp_lt_i32_e32 vcc, v3, v4
	v_sub_f32_e32 v2, v210, v222
	s_nop 0
	v_cndmask_b32_e32 v3, v188, v3, vcc
	v_lshlrev_b32_e32 v3, 2, v3
	ds_bpermute_b32 v3, v3, v2
	s_waitcnt lgkmcnt(0)
	v_max_f32_e32 v3, v3, v3
	v_max_f32_e32 v2, v2, v3
	v_xor_b32_e32 v3, 8, v188
	v_cmp_lt_i32_e32 vcc, v3, v4
	s_nop 1
	v_cndmask_b32_e32 v3, v188, v3, vcc
	v_lshlrev_b32_e32 v3, 2, v3
	ds_bpermute_b32 v3, v3, v2
	s_waitcnt lgkmcnt(0)
	v_max_f32_e32 v3, v3, v3
	v_max_f32_e32 v2, v2, v3
	v_xor_b32_e32 v3, 4, v188
	v_cmp_lt_i32_e32 vcc, v3, v4
	s_nop 1
	v_cndmask_b32_e32 v3, v188, v3, vcc
	v_lshlrev_b32_e32 v3, 2, v3
	ds_bpermute_b32 v3, v3, v2
	s_waitcnt lgkmcnt(0)
	v_max_f32_e32 v3, v3, v3
	v_max_f32_e32 v2, v2, v3
	v_xor_b32_e32 v3, 2, v188
	v_cmp_lt_i32_e32 vcc, v3, v4
	s_nop 1
	v_cndmask_b32_e32 v3, v188, v3, vcc
	v_lshlrev_b32_e32 v3, 2, v3
	ds_bpermute_b32 v3, v3, v2
	s_waitcnt lgkmcnt(0)
	v_max_f32_e32 v3, v3, v3
	v_max_f32_e32 v2, v2, v3
	v_xor_b32_e32 v3, 1, v188
	v_cmp_lt_i32_e32 vcc, v3, v4
	s_nop 1
	v_cndmask_b32_e32 v3, v188, v3, vcc
	v_lshlrev_b32_e32 v3, 2, v3
	ds_bpermute_b32 v3, v3, v2
	s_waitcnt lgkmcnt(0)
	v_max_f32_e32 v3, v3, v3
	v_max_f32_e32 v219, v2, v3

.LBB0_443:
	s_or_b64 exec, exec, s[28:29]
	s_nop 6
	v_max3_f32 v0, v80, v81, v82
	v_max3_f32 v2, v83, v84, v85
	v_max3_f32 v3, v86, v87, v88
	v_max3_f32 v4, v89, v90, v91
	v_max3_f32 v5, v92, v93, v94
	v_max3_f32 v6, v95, v96, v97
	v_max3_f32 v7, v98, v99, v100
	v_max3_f32 v8, v101, v102, v103
	v_max3_f32 v9, v104, v105, v106
	v_max3_f32 v10, v107, v108, v109
	v_max3_f32 v11, v110, v111, v0
	v_max3_f32 v2, v2, v3, v4
	v_max3_f32 v5, v5, v6, v7
	v_max3_f32 v8, v8, v9, v10
	v_max3_f32 v2, v2, v5, v8
	v_max_f32_e32 v0, v2, v11
	v_mov_b32_e32 v2, v0
	s_nop 1
	v_permlane32_swap_b32_e32 v0, v2
	v_max3_f32 v215, v214, v0, v2
	v_sub_f32_e32 v0, v214, v215
	v_exp_f32_e32 v0, v0
	s_nop 0
	v_cmp_eq_f32_e32 vcc, 1.0, v0
	s_cmp_lg_u64 vcc, exec
	s_cselect_b64 s[28:29], -1, 0
	s_cmp_eq_u64 vcc, exec
	s_cbranch_scc1 .LBB0_445
	v_and_b32_e32 v4, 64, v188
	v_xor_b32_e32 v3, 16, v188
	v_add_u32_e32 v4, 64, v4
	v_cmp_lt_i32_e32 vcc, v3, v4
	v_sub_f32_e32 v2, v202, v215
	s_nop 0
	v_cndmask_b32_e32 v3, v188, v3, vcc
	v_lshlrev_b32_e32 v3, 2, v3
	ds_bpermute_b32 v3, v3, v2
	s_waitcnt lgkmcnt(0)
	v_max_f32_e32 v3, v3, v3
	v_max_f32_e32 v2, v2, v3
	v_xor_b32_e32 v3, 8, v188
	v_cmp_lt_i32_e32 vcc, v3, v4
	s_nop 1
	v_cndmask_b32_e32 v3, v188, v3, vcc
	v_lshlrev_b32_e32 v3, 2, v3
	ds_bpermute_b32 v3, v3, v2
	s_waitcnt lgkmcnt(0)
	v_max_f32_e32 v3, v3, v3
	v_max_f32_e32 v2, v2, v3
	v_xor_b32_e32 v3, 4, v188
	v_cmp_lt_i32_e32 vcc, v3, v4
	s_nop 1
	v_cndmask_b32_e32 v3, v188, v3, vcc
	v_lshlrev_b32_e32 v3, 2, v3
	ds_bpermute_b32 v3, v3, v2
	s_waitcnt lgkmcnt(0)
	v_max_f32_e32 v3, v3, v3
	v_max_f32_e32 v2, v2, v3
	v_xor_b32_e32 v3, 2, v188
	v_cmp_lt_i32_e32 vcc, v3, v4
	s_nop 1
	v_cndmask_b32_e32 v3, v188, v3, vcc
	v_lshlrev_b32_e32 v3, 2, v3
	ds_bpermute_b32 v3, v3, v2
	s_waitcnt lgkmcnt(0)
	v_max_f32_e32 v3, v3, v3
	v_max_f32_e32 v2, v2, v3
	v_xor_b32_e32 v3, 1, v188
	v_cmp_lt_i32_e32 vcc, v3, v4
	s_nop 1
	v_cndmask_b32_e32 v3, v188, v3, vcc
	v_lshlrev_b32_e32 v3, 2, v3
	ds_bpermute_b32 v3, v3, v2
	s_waitcnt lgkmcnt(0)
	v_max_f32_e32 v3, v3, v3
	v_max_f32_e32 v212, v2, v3

.LBB0_627:
	s_or_b64 exec, exec, s[2:3]
	v_lshlrev_b32_e32 v110, 16, v116
	v_and_b32_e32 v111, 0xffff0000, v116
	v_pk_mul_f32 v[162:163], v[110:111], s[10:11] op_sel_hi:[1,0]
	v_lshlrev_b32_e32 v164, 16, v117
	v_exp_f32_e32 v162, v162
	v_exp_f32_e32 v163, v163
	v_and_b32_e32 v165, 0xffff0000, v117
	v_pk_mul_f32 v[116:117], v[164:165], s[10:11] op_sel_hi:[1,0]
	v_pk_mul_f32 v[110:111], v[132:133], v[110:111]
	v_pk_add_f32 v[162:163], v[162:163], 1.0 op_sel_hi:[1,0]
	v_exp_f32_e32 v216, v116
	v_rcp_f32_e32 v162, v162
	v_rcp_f32_e32 v163, v163
	v_exp_f32_e32 v217, v117
	v_lshlrev_b32_e32 v132, 16, v118
	v_and_b32_e32 v133, 0xffff0000, v118
	v_pk_mul_f32 v[110:111], v[162:163], v[110:111]
	v_pk_mul_f32 v[162:163], v[132:133], s[10:11] op_sel_hi:[1,0]
	v_cvt_pk_bf16_f32 v116, v110, v111
	v_pk_add_f32 v[110:111], v[216:217], 1.0 op_sel_hi:[1,0]
	v_exp_f32_e32 v162, v162
	v_rcp_f32_e32 v110, v110
	v_rcp_f32_e32 v111, v111
	v_exp_f32_e32 v163, v163
	v_pk_mul_f32 v[134:135], v[134:135], v[164:165]
	s_add_i32 s17, s17, 32
	v_pk_mul_f32 v[110:111], v[110:111], v[134:135]
	v_lshlrev_b32_e32 v134, 16, v119
	v_cvt_pk_bf16_f32 v117, v110, v111
	v_pk_add_f32 v[110:111], v[162:163], 1.0 op_sel_hi:[1,0]
	v_and_b32_e32 v135, 0xffff0000, v119
	v_rcp_f32_e32 v110, v110
	v_rcp_f32_e32 v111, v111
	v_pk_mul_f32 v[118:119], v[134:135], s[10:11] op_sel_hi:[1,0]
	v_pk_mul_f32 v[130:131], v[130:131], v[134:135]
	v_exp_f32_e32 v162, v118
	v_exp_f32_e32 v163, v119
	v_pk_mul_f32 v[118:119], v[128:129], v[132:133]
	v_lshlrev_b32_e32 v128, 16, v112
	v_pk_mul_f32 v[110:111], v[110:111], v[118:119]
	v_and_b32_e32 v129, 0xffff0000, v112
	v_cvt_pk_bf16_f32 v118, v110, v111
	v_pk_add_f32 v[110:111], v[162:163], 1.0 op_sel_hi:[1,0]
	v_pk_mul_f32 v[132:133], v[128:129], s[10:11] op_sel_hi:[1,0]
	v_rcp_f32_e32 v110, v110
	v_rcp_f32_e32 v111, v111
	v_exp_f32_e32 v132, v132
	v_exp_f32_e32 v133, v133
	v_lshlrev_b32_e32 v112, 16, v113
	v_pk_mul_f32 v[110:111], v[110:111], v[130:131]
	v_and_b32_e32 v113, 0xffff0000, v113
	v_cvt_pk_bf16_f32 v119, v110, v111
	v_pk_add_f32 v[110:111], v[132:133], 1.0 op_sel_hi:[1,0]
	v_pk_mul_f32 v[130:131], v[112:113], s[10:11] op_sel_hi:[1,0]
	v_rcp_f32_e32 v110, v110
	v_rcp_f32_e32 v111, v111
	v_exp_f32_e32 v130, v130
	v_exp_f32_e32 v131, v131
	v_pk_mul_f32 v[124:125], v[124:125], v[128:129]
	v_lshlrev_b32_e32 v128, 16, v114
	v_pk_mul_f32 v[110:111], v[110:111], v[124:125]
	v_pk_add_f32 v[124:125], v[130:131], 1.0 op_sel_hi:[1,0]
	v_and_b32_e32 v129, 0xffff0000, v114
	v_rcp_f32_e32 v124, v124
	v_rcp_f32_e32 v125, v125
	v_pk_mul_f32 v[112:113], v[126:127], v[112:113]
	v_lshlrev_b32_e32 v114, 16, v115
	v_and_b32_e32 v115, 0xffff0000, v115
	v_pk_mul_f32 v[130:131], v[128:129], s[10:11] op_sel_hi:[1,0]
	v_pk_mul_f32 v[112:113], v[124:125], v[112:113]
	v_pk_mul_f32 v[124:125], v[114:115], s[10:11] op_sel_hi:[1,0]
	v_exp_f32_e32 v130, v130
	v_exp_f32_e32 v131, v131
	v_exp_f32_e32 v124, v124
	v_exp_f32_e32 v125, v125
	v_cvt_pk_bf16_f32 v110, v110, v111
	v_cvt_pk_bf16_f32 v111, v112, v113
	v_pk_add_f32 v[112:113], v[130:131], 1.0 op_sel_hi:[1,0]
	v_pk_add_f32 v[124:125], v[124:125], 1.0 op_sel_hi:[1,0]
	v_rcp_f32_e32 v112, v112
	v_rcp_f32_e32 v113, v113
	v_rcp_f32_e32 v124, v124
	v_rcp_f32_e32 v125, v125
	v_pk_mul_f32 v[120:121], v[120:121], v[128:129]
	v_pk_mul_f32 v[114:115], v[122:123], v[114:115]
	v_pk_mul_f32 v[112:113], v[112:113], v[120:121]
	v_pk_mul_f32 v[114:115], v[124:125], v[114:115]
	v_cvt_pk_bf16_f32 v112, v112, v113
	v_cvt_pk_bf16_f32 v113, v114, v115
	v_lshlrev_b64 v[114:115], 12, v[148:149]
	s_addk_i32 s11, 0x800
	v_lshl_add_u64 v[114:115], v[146:147], 0, v[114:115]
	s_cmpk_eq_i32 s11, 0x4800
	v_add_u32_e32 v212, 0x200, v212
	global_store_dwordx4 v[114:115], v[116:119], off offset:2048
	global_store_dwordx4 v[114:115], v[110:113], off offset:2064
	s_cbranch_scc1 .LBB0_654
.LBB0_628:
	s_sub_i32 s2, s17, 32
	s_and_b32 s2, s2, 0x60
	s_add_i32 s2, s2, s87
	s_add_i32 s3, s11, 0xfffff800
	s_lshl_b32 s2, s2, 6
	s_and_b32 s3, s3, 0x2000
	s_add_i32 s14, s2, s3
	v_lshl_add_u64 v[148:149], s[14:15], 0, v[90:91]
	v_lshlrev_b64 v[110:111], 11, v[148:149]
	v_lshl_add_u64 v[110:111], v[144:145], 0, v[110:111]
	global_load_dwordx4 v[112:115], v[110:111], off offset:16 nt
	global_load_dwordx4 v[116:119], v[110:111], off nt
	v_lshlrev_b32_e32 v110, 16, v76
	v_and_b32_e32 v111, 0xffff0000, v76
	v_pk_fma_f32 v[110:111], v[68:69], v[110:111], v[72:73]
	v_lshlrev_b32_e32 v120, 16, v77
	v_and_b32_e32 v121, 0xffff0000, v77
	v_lshlrev_b32_e32 v126, 16, v32
	v_and_b32_e32 v127, 0xffff0000, v32
	v_pk_fma_f32 v[120:121], v[70:71], v[120:121], v[74:75]
	v_lshlrev_b32_e32 v122, 16, v78
	v_and_b32_e32 v123, 0xffff0000, v78
	v_pk_fma_f32 v[110:111], v[36:37], v[126:127], v[110:111]
	v_lshlrev_b32_e32 v126, 16, v33
	v_and_b32_e32 v127, 0xffff0000, v33
	v_pk_fma_f32 v[122:123], v[60:61], v[122:123], v[64:65]
	v_lshlrev_b32_e32 v124, 16, v79
	v_and_b32_e32 v125, 0xffff0000, v79
	v_pk_fma_f32 v[120:121], v[38:39], v[126:127], v[120:121]
	v_lshlrev_b32_e32 v126, 16, v34
	v_and_b32_e32 v127, 0xffff0000, v34
	v_pk_fma_f32 v[124:125], v[62:63], v[124:125], v[66:67]
	v_pk_fma_f32 v[122:123], v[44:45], v[126:127], v[122:123]
	v_lshlrev_b32_e32 v126, 16, v35
	v_and_b32_e32 v127, 0xffff0000, v35
	v_pk_fma_f32 v[124:125], v[46:47], v[126:127], v[124:125]
	v_lshlrev_b32_e32 v126, 16, v80
	v_and_b32_e32 v127, 0xffff0000, v80
	v_pk_fma_f32 v[110:111], v[40:41], v[126:127], v[110:111]
	v_lshlrev_b32_e32 v126, 16, v81
	v_and_b32_e32 v127, 0xffff0000, v81
	v_pk_fma_f32 v[126:127], v[42:43], v[126:127], v[120:121]
	v_lshlrev_b32_e32 v120, 16, v82
	v_and_b32_e32 v121, 0xffff0000, v82
	v_pk_fma_f32 v[128:129], v[48:49], v[120:121], v[122:123]
	v_lshlrev_b32_e32 v120, 16, v83
	v_and_b32_e32 v121, 0xffff0000, v83
	v_pk_fma_f32 v[130:131], v[50:51], v[120:121], v[124:125]
	v_lshlrev_b32_e32 v120, 16, v84
	v_and_b32_e32 v121, 0xffff0000, v84
	v_pk_fma_f32 v[120:121], v[52:53], v[120:121], v[110:111]
	v_lshlrev_b32_e32 v110, 16, v85
	v_and_b32_e32 v111, 0xffff0000, v85
	v_pk_fma_f32 v[122:123], v[54:55], v[110:111], v[126:127]
	v_lshlrev_b32_e32 v110, 16, v86
	v_and_b32_e32 v111, 0xffff0000, v86
	v_pk_fma_f32 v[124:125], v[56:57], v[110:111], v[128:129]
	v_lshlrev_b32_e32 v110, 16, v87
	v_and_b32_e32 v111, 0xffff0000, v87
	v_pk_fma_f32 v[126:127], v[58:59], v[110:111], v[130:131]
	v_add_u32_e32 v88, v153, v158
	ds_write_b128 v88, v[120:123] offset:17408
	ds_write_b128 v88, v[124:127] offset:17424
	v_cvt_pk_bf16_f32 v120, v120, v121
	v_cvt_pk_bf16_f32 v121, v122, v123
	v_cvt_pk_bf16_f32 v122, v124, v125
	v_cvt_pk_bf16_f32 v123, v126, v127
	v_lshlrev_b32_e32 v110, 16, v92
	v_and_b32_e32 v111, 0xffff0000, v92
	ds_write_b128 v213, v[120:123]
	v_pk_fma_f32 v[110:111], v[68:69], v[110:111], v[72:73]
	v_lshlrev_b32_e32 v120, 16, v93
	v_and_b32_e32 v121, 0xffff0000, v93
	v_lshlrev_b32_e32 v126, 16, v96
	v_and_b32_e32 v127, 0xffff0000, v96
	v_pk_fma_f32 v[120:121], v[70:71], v[120:121], v[74:75]
	v_lshlrev_b32_e32 v122, 16, v94
	v_and_b32_e32 v123, 0xffff0000, v94
	v_pk_fma_f32 v[110:111], v[36:37], v[126:127], v[110:111]
	v_lshlrev_b32_e32 v126, 16, v97
	v_and_b32_e32 v127, 0xffff0000, v97
	v_pk_fma_f32 v[122:123], v[60:61], v[122:123], v[64:65]
	v_lshlrev_b32_e32 v124, 16, v95
	v_and_b32_e32 v125, 0xffff0000, v95
	v_pk_fma_f32 v[120:121], v[38:39], v[126:127], v[120:121]
	v_lshlrev_b32_e32 v126, 16, v98
	v_and_b32_e32 v127, 0xffff0000, v98
	v_pk_fma_f32 v[124:125], v[62:63], v[124:125], v[66:67]
	v_pk_fma_f32 v[122:123], v[44:45], v[126:127], v[122:123]
	v_lshlrev_b32_e32 v126, 16, v99
	v_and_b32_e32 v127, 0xffff0000, v99
	v_pk_fma_f32 v[124:125], v[46:47], v[126:127], v[124:125]
	v_lshlrev_b32_e32 v126, 16, v100
	v_and_b32_e32 v127, 0xffff0000, v100
	v_pk_fma_f32 v[110:111], v[40:41], v[126:127], v[110:111]
	v_lshlrev_b32_e32 v126, 16, v101
	v_and_b32_e32 v127, 0xffff0000, v101
	v_pk_fma_f32 v[126:127], v[42:43], v[126:127], v[120:121]
	v_lshlrev_b32_e32 v120, 16, v102
	v_and_b32_e32 v121, 0xffff0000, v102
	v_pk_fma_f32 v[128:129], v[48:49], v[120:121], v[122:123]
	v_lshlrev_b32_e32 v120, 16, v103
	v_and_b32_e32 v121, 0xffff0000, v103
	v_pk_fma_f32 v[130:131], v[50:51], v[120:121], v[124:125]
	v_lshlrev_b32_e32 v120, 16, v104
	v_and_b32_e32 v121, 0xffff0000, v104
	v_pk_fma_f32 v[120:121], v[52:53], v[120:121], v[110:111]
	v_lshlrev_b32_e32 v110, 16, v105
	v_and_b32_e32 v111, 0xffff0000, v105
	v_pk_fma_f32 v[122:123], v[54:55], v[110:111], v[126:127]
	v_lshlrev_b32_e32 v110, 16, v106
	v_and_b32_e32 v111, 0xffff0000, v106
	v_pk_fma_f32 v[124:125], v[56:57], v[110:111], v[128:129]
	v_lshlrev_b32_e32 v110, 16, v107
	v_and_b32_e32 v111, 0xffff0000, v107
	v_pk_fma_f32 v[126:127], v[58:59], v[110:111], v[130:131]
	ds_write_b128 v214, v[120:123] offset:17408
	ds_write_b128 v214, v[124:127] offset:17424
	v_cvt_pk_bf16_f32 v120, v120, v121
	v_cvt_pk_bf16_f32 v121, v122, v123
	v_cvt_pk_bf16_f32 v122, v124, v125
	v_cvt_pk_bf16_f32 v123, v126, v127
	s_cmpk_eq_i32 s11, 0x4000
	ds_write_b128 v213, v[120:123] offset:8704
	s_cbranch_scc1 .LBB0_646
	s_and_b32 s2, s17, 0x60
	s_add_i32 s2, s2, s87
	s_lshl_b32 s20, s2, 6
	s_and_b32 s14, s11, 0x6000
	s_cmp_eq_u32 s20, 0
	s_cbranch_scc1 .Llru2_pf_slow
	s_add_i32 s2, s20, s14
	v_add_u32_e32 v88, s2, v152
	v_lshlrev_b64 v[84:85], 11, v[88:89]
	s_mov_b64 s[2:3], 0x1000
	v_lshl_add_u64 v[84:85], v[136:137], 0, v[84:85]
	s_mov_b64 s[8:9], 0x10000
	v_lshl_add_u64 v[84:85], v[84:85], 0, s[2:3]
	v_lshl_add_u64 v[104:105], v[84:85], 0, s[8:9]
	global_load_dwordx4 v[76:79], v[84:85], off offset:-4096 nt
	global_load_dwordx4 v[32:35], v[84:85], off offset:-2048 nt
	global_load_dwordx4 v[80:83], v[84:85], off nt
	global_load_dwordx4 v[84:87], v[84:85], off offset:2048 nt
	global_load_dwordx4 v[92:95], v[104:105], off offset:-4096 nt
	global_load_dwordx4 v[96:99], v[104:105], off offset:-2048 nt
	global_load_dwordx4 v[100:103], v[104:105], off nt
	global_load_dwordx4 v[104:107], v[104:105], off offset:2048 nt
	s_branch .LBB0_646
.Llru2_pf_slow:
	v_mov_b32_e32 v34, v108
	v_mov_b32_e32 v35, v108
	v_add_u32_e32 v104, s20, v152
	v_mov_b32_e32 v32, v108
	v_mov_b32_e32 v33, v108
	v_mov_b64_e32 v[78:79], v[34:35]
	s_and_b32 s14, s11, 0x6000
	v_cmp_lt_i32_e64 s[8:9], -1, v104
	v_mov_b64_e32 v[76:77], v[32:33]
	s_and_saveexec_b64 s[2:3], s[8:9]
	s_cbranch_execz .LBB0_631
	v_add_u32_e32 v88, s14, v104
	v_lshlrev_b64 v[76:77], 11, v[88:89]
	v_lshl_add_u64 v[76:77], v[136:137], 0, v[76:77]
	global_load_dwordx4 v[76:79], v[76:77], off nt

.LBB0_650:
	s_or_b64 exec, exec, s[2:3]
	ds_read2st64_b32 v[110:111], v184 offset0:196 offset1:198
	ds_read2st64_b32 v[120:121], v184 offset0:200 offset1:202
	ds_read_b32 v109, v185
	ds_read_b32 v122, v186
	ds_read_b32 v123, v187
	ds_read_b32 v124, v189
	ds_read_b32 v125, v190
	ds_read_b32 v126, v191
	ds_read_b32 v127, v192
	ds_read_b32 v128, v193
	s_waitcnt lgkmcnt(7)
	v_fmac_f32_e32 v109, v88, v110
	s_waitcnt lgkmcnt(6)
	v_fmac_f32_e32 v122, v109, v111
	ds_read2st64_b32 v[110:111], v184 offset0:204 offset1:206
	s_waitcnt lgkmcnt(6)
	v_fmac_f32_e32 v123, v122, v120
	s_waitcnt lgkmcnt(5)
	v_fmac_f32_e32 v124, v123, v121
	ds_read2st64_b32 v[120:121], v184 offset0:208 offset1:210
	ds_write_b32 v185, v109
	s_waitcnt lgkmcnt(2)
	v_fmac_f32_e32 v125, v124, v110
	v_fmac_f32_e32 v126, v125, v111
	ds_write_b32 v186, v122
	s_waitcnt lgkmcnt(2)
	v_fmac_f32_e32 v127, v126, v120
	v_fmac_f32_e32 v128, v127, v121
	ds_write_b32 v187, v123
	ds_write_b32 v189, v124
	ds_write_b32 v190, v125
	ds_write_b32 v191, v126
	ds_write_b32 v192, v127
	ds_write_b32 v193, v128
	ds_read2st64_b32 v[110:111], v184 offset0:212 offset1:214
	ds_read2st64_b32 v[120:121], v184 offset0:216 offset1:218
	ds_read_b32 v88, v194
	ds_read_b32 v109, v195
	ds_read_b32 v122, v196
	ds_read_b32 v123, v197
	ds_read_b32 v124, v198
	ds_read_b32 v125, v199
	ds_read_b32 v126, v200
	ds_read_b32 v127, v201
	s_waitcnt lgkmcnt(7)
	v_fmac_f32_e32 v88, v128, v110
	s_waitcnt lgkmcnt(6)
	v_fmac_f32_e32 v109, v88, v111
	ds_read2st64_b32 v[110:111], v184 offset0:220 offset1:222
	s_waitcnt lgkmcnt(6)
	v_fmac_f32_e32 v122, v109, v120
	s_waitcnt lgkmcnt(5)
	v_fmac_f32_e32 v123, v122, v121
	ds_read2st64_b32 v[120:121], v184 offset0:224 offset1:226
	ds_write_b32 v194, v88
	s_waitcnt lgkmcnt(2)
	v_fmac_f32_e32 v124, v123, v110
	v_fmac_f32_e32 v125, v124, v111
	ds_write_b32 v195, v109
	s_waitcnt lgkmcnt(2)
	v_fmac_f32_e32 v126, v125, v120
	v_fmac_f32_e32 v127, v126, v121
	ds_write_b32 v196, v122
	ds_write_b32 v197, v123
	ds_write_b32 v198, v124
	ds_write_b32 v199, v125
	ds_write_b32 v200, v126
	ds_write_b32 v201, v127
	s_waitcnt lgkmcnt(0)
	s_barrier
	ds_read_b128 v[132:135], v157
	ds_read_b128 v[128:131], v157 offset:16
	ds_read_b128 v[124:127], v157 offset:32
	ds_read_b128 v[120:123], v157 offset:48
	s_waitcnt lgkmcnt(3)
	v_mul_f32_e32 v88, v133, v133
	v_fmac_f32_e32 v88, v132, v132
	v_fmac_f32_e32 v88, v134, v134
	v_fmac_f32_e32 v88, v135, v135
	s_waitcnt lgkmcnt(2)
	v_fmac_f32_e32 v88, v128, v128
	v_fmac_f32_e32 v88, v129, v129
	v_fmac_f32_e32 v88, v130, v130
	v_fmac_f32_e32 v88, v131, v131
	s_waitcnt lgkmcnt(1)
	v_fmac_f32_e32 v88, v124, v124
	v_fmac_f32_e32 v88, v125, v125
	v_fmac_f32_e32 v88, v126, v126
	v_fmac_f32_e32 v88, v127, v127
	s_waitcnt lgkmcnt(0)
	v_fmac_f32_e32 v88, v120, v120
	v_fmac_f32_e32 v88, v121, v121
	v_fmac_f32_e32 v88, v122, v122
	v_fmac_f32_e32 v88, v123, v123
	ds_bpermute_b32 v109, v205, v88
	s_waitcnt lgkmcnt(0)
	v_add_f32_e32 v88, v88, v109
	ds_bpermute_b32 v109, v206, v88
	s_waitcnt lgkmcnt(0)
	v_add_f32_e32 v88, v88, v109
	ds_bpermute_b32 v109, v207, v88
	s_waitcnt vmcnt(0)
	s_and_saveexec_b64 s[2:3], vcc
	s_cbranch_execz .LBB0_627
	v_lshl_add_u64 v[110:111], v[148:149], 2, s[18:19]
	s_waitcnt lgkmcnt(0)
	v_add_f32_e32 v88, v88, v109
	global_atomic_add_f32 v[110:111], v88, off
	s_branch .LBB0_627
